# P1 weight-copy stores with nt (as the source intends: the copies are first read phases later), keeps them out of the GEMM workgroups' L2
# baseline (speedup 1.0000x reference)
.LBB0_249:
	v_cndmask_b32_e64 v128, v156, v158, s[14:15]
	v_lshl_add_u32 v192, v128, 2, v157
	ds_read2_b32 v[128:129], v192 offset1:65
	ds_read2_b32 v[130:131], v192 offset0:130 offset1:195
	v_add_u32_e32 v192, 0x400, v192
	s_waitcnt lgkmcnt(1)
	v_cvt_pk_bf16_f32 v128, v128, v129
	s_waitcnt lgkmcnt(0)
	v_cvt_pk_bf16_f32 v129, v130, v131
	ds_read2_b32 v[130:131], v192 offset0:4 offset1:69
	ds_read2_b32 v[192:193], v192 offset0:134 offset1:199
	s_waitcnt lgkmcnt(1)
	v_cvt_pk_bf16_f32 v130, v130, v131
	s_waitcnt lgkmcnt(0)
	v_cvt_pk_bf16_f32 v131, v192, v193
	v_add_u32_e32 v192, s31, v156
	v_mad_i64_i32 v[192:193], s[0:1], v192, s51, 0
	v_lshl_add_u64 v[192:193], v[192:193], 1, s[4:5]
	s_lshl_b64 s[0:1], s[12:13], 1
	v_lshl_add_u64 v[192:193], v[192:193], 0, s[0:1]
	v_lshl_add_u64 v[192:193], v[192:193], 0, v[136:137]
	global_store_dwordx4 v[192:193], v[128:131], off nt
	s_nop 1
	v_cndmask_b32_e64 v128, v159, v160, s[14:15]
	v_lshl_add_u32 v192, v128, 2, v157
	ds_read2_b32 v[128:129], v192 offset1:65
	ds_read2_b32 v[130:131], v192 offset0:130 offset1:195
	v_add_u32_e32 v192, 0x400, v192
	s_waitcnt lgkmcnt(1)
	v_cvt_pk_bf16_f32 v128, v128, v129
	s_waitcnt lgkmcnt(0)
	v_cvt_pk_bf16_f32 v129, v130, v131
	ds_read2_b32 v[130:131], v192 offset0:4 offset1:69
	ds_read2_b32 v[192:193], v192 offset0:134 offset1:199
	s_waitcnt lgkmcnt(1)
	v_cvt_pk_bf16_f32 v130, v130, v131
	s_waitcnt lgkmcnt(0)
	v_cvt_pk_bf16_f32 v131, v192, v193
	v_add_u32_e32 v192, s31, v159
	v_mad_i64_i32 v[192:193], s[16:17], v192, s51, 0
	v_lshl_add_u64 v[192:193], v[192:193], 1, s[4:5]
	v_lshl_add_u64 v[192:193], v[192:193], 0, s[0:1]
	v_lshl_add_u64 v[192:193], v[192:193], 0, v[136:137]
	global_store_dwordx4 v[192:193], v[128:131], off nt
	s_nop 1
	v_cndmask_b32_e64 v128, v161, v162, s[14:15]
	v_lshl_add_u32 v192, v128, 2, v157
	ds_read2_b32 v[128:129], v192 offset1:65
	ds_read2_b32 v[130:131], v192 offset0:130 offset1:195
	v_add_u32_e32 v192, 0x400, v192
	s_waitcnt lgkmcnt(1)
	v_cvt_pk_bf16_f32 v128, v128, v129
	s_waitcnt lgkmcnt(0)
	v_cvt_pk_bf16_f32 v129, v130, v131
	ds_read2_b32 v[130:131], v192 offset0:4 offset1:69
	ds_read2_b32 v[192:193], v192 offset0:134 offset1:199
	s_waitcnt lgkmcnt(1)
	v_cvt_pk_bf16_f32 v130, v130, v131
	s_waitcnt lgkmcnt(0)
	v_cvt_pk_bf16_f32 v131, v192, v193
	v_add_u32_e32 v192, s31, v161
	v_mad_i64_i32 v[192:193], s[16:17], v192, s51, 0
	v_lshl_add_u64 v[192:193], v[192:193], 1, s[4:5]
	v_lshl_add_u64 v[192:193], v[192:193], 0, s[0:1]
	v_lshl_add_u64 v[192:193], v[192:193], 0, v[136:137]
	global_store_dwordx4 v[192:193], v[128:131], off nt
	s_nop 1
	v_cndmask_b32_e64 v128, v163, v164, s[14:15]
	v_lshl_add_u32 v192, v128, 2, v157
	ds_read2_b32 v[128:129], v192 offset1:65
	ds_read2_b32 v[130:131], v192 offset0:130 offset1:195
	v_add_u32_e32 v192, 0x400, v192
	s_waitcnt lgkmcnt(1)
	v_cvt_pk_bf16_f32 v128, v128, v129
	s_waitcnt lgkmcnt(0)
	v_cvt_pk_bf16_f32 v129, v130, v131
	ds_read2_b32 v[130:131], v192 offset0:4 offset1:69
	ds_read2_b32 v[192:193], v192 offset0:134 offset1:199
	s_waitcnt lgkmcnt(1)
	v_cvt_pk_bf16_f32 v130, v130, v131
	s_waitcnt lgkmcnt(0)
	v_cvt_pk_bf16_f32 v131, v192, v193
	v_add_u32_e32 v192, s31, v163
	v_mad_i64_i32 v[192:193], s[16:17], v192, s51, 0
	v_lshl_add_u64 v[192:193], v[192:193], 1, s[4:5]
	v_lshl_add_u64 v[192:193], v[192:193], 0, s[0:1]
	v_lshl_add_u64 v[192:193], v[192:193], 0, v[136:137]
	global_store_dwordx4 v[192:193], v[128:131], off nt
	s_nop 1
	v_cndmask_b32_e64 v128, v165, v166, s[14:15]
	v_lshl_add_u32 v192, v128, 2, v157
	ds_read2_b32 v[128:129], v192 offset1:65
	ds_read2_b32 v[130:131], v192 offset0:130 offset1:195
	v_add_u32_e32 v192, 0x400, v192
	s_waitcnt lgkmcnt(1)
	v_cvt_pk_bf16_f32 v128, v128, v129
	s_waitcnt lgkmcnt(0)
	v_cvt_pk_bf16_f32 v129, v130, v131
	ds_read2_b32 v[130:131], v192 offset0:4 offset1:69
	ds_read2_b32 v[192:193], v192 offset0:134 offset1:199
	s_waitcnt lgkmcnt(1)
	v_cvt_pk_bf16_f32 v130, v130, v131
	s_waitcnt lgkmcnt(0)
	v_cvt_pk_bf16_f32 v131, v192, v193
	v_add_u32_e32 v192, s31, v165
	v_mad_i64_i32 v[192:193], s[16:17], v192, s51, 0
	v_lshl_add_u64 v[192:193], v[192:193], 1, s[4:5]
	v_lshl_add_u64 v[192:193], v[192:193], 0, s[0:1]
	v_lshl_add_u64 v[192:193], v[192:193], 0, v[136:137]
	global_store_dwordx4 v[192:193], v[128:131], off nt
	s_nop 1
	v_cndmask_b32_e64 v128, v167, v168, s[14:15]
	v_lshl_add_u32 v192, v128, 2, v157
	ds_read2_b32 v[128:129], v192 offset1:65
	ds_read2_b32 v[130:131], v192 offset0:130 offset1:195
	v_add_u32_e32 v192, 0x400, v192
	s_waitcnt lgkmcnt(1)
	v_cvt_pk_bf16_f32 v128, v128, v129
	s_waitcnt lgkmcnt(0)
	v_cvt_pk_bf16_f32 v129, v130, v131
	ds_read2_b32 v[130:131], v192 offset0:4 offset1:69
	ds_read2_b32 v[192:193], v192 offset0:134 offset1:199
	s_waitcnt lgkmcnt(1)
	v_cvt_pk_bf16_f32 v130, v130, v131
	s_waitcnt lgkmcnt(0)
	v_cvt_pk_bf16_f32 v131, v192, v193
	v_add_u32_e32 v192, s31, v167
	v_mad_i64_i32 v[192:193], s[16:17], v192, s51, 0
	v_lshl_add_u64 v[192:193], v[192:193], 1, s[4:5]
	v_lshl_add_u64 v[192:193], v[192:193], 0, s[0:1]
	v_lshl_add_u64 v[192:193], v[192:193], 0, v[136:137]
	global_store_dwordx4 v[192:193], v[128:131], off nt
	s_nop 1
	v_cndmask_b32_e64 v128, v169, v170, s[14:15]
	v_lshl_add_u32 v192, v128, 2, v157
	ds_read2_b32 v[128:129], v192 offset1:65
	ds_read2_b32 v[130:131], v192 offset0:130 offset1:195
	v_add_u32_e32 v192, 0x400, v192
	s_waitcnt lgkmcnt(1)
	v_cvt_pk_bf16_f32 v128, v128, v129
	s_waitcnt lgkmcnt(0)
	v_cvt_pk_bf16_f32 v129, v130, v131
	ds_read2_b32 v[130:131], v192 offset0:4 offset1:69
	ds_read2_b32 v[192:193], v192 offset0:134 offset1:199
	s_waitcnt lgkmcnt(1)
	v_cvt_pk_bf16_f32 v130, v130, v131
	s_waitcnt lgkmcnt(0)
	v_cvt_pk_bf16_f32 v131, v192, v193
	v_add_u32_e32 v192, s31, v169
	v_mad_i64_i32 v[192:193], s[16:17], v192, s51, 0
	v_lshl_add_u64 v[192:193], v[192:193], 1, s[4:5]
	v_lshl_add_u64 v[192:193], v[192:193], 0, s[0:1]
	v_lshl_add_u64 v[192:193], v[192:193], 0, v[136:137]
	global_store_dwordx4 v[192:193], v[128:131], off nt
	s_nop 1
	v_cndmask_b32_e64 v128, v171, v172, s[14:15]
	v_lshl_add_u32 v192, v128, 2, v157
	ds_read2_b32 v[128:129], v192 offset1:65
	ds_read2_b32 v[130:131], v192 offset0:130 offset1:195
	v_add_u32_e32 v192, 0x400, v192
	s_waitcnt lgkmcnt(1)
	v_cvt_pk_bf16_f32 v128, v128, v129
	s_waitcnt lgkmcnt(0)
	v_cvt_pk_bf16_f32 v129, v130, v131
	ds_read2_b32 v[130:131], v192 offset0:4 offset1:69
	ds_read2_b32 v[192:193], v192 offset0:134 offset1:199
	s_waitcnt lgkmcnt(1)
	v_cvt_pk_bf16_f32 v130, v130, v131
	s_waitcnt lgkmcnt(0)
	v_cvt_pk_bf16_f32 v131, v192, v193
	v_add_u32_e32 v192, s31, v171
	v_mad_i64_i32 v[192:193], s[16:17], v192, s51, 0
	v_lshl_add_u64 v[192:193], v[192:193], 1, s[4:5]
	v_lshl_add_u64 v[192:193], v[192:193], 0, s[0:1]
	v_lshl_add_u64 v[192:193], v[192:193], 0, v[136:137]
	global_store_dwordx4 v[192:193], v[128:131], off nt
	s_waitcnt lgkmcnt(0)

.LBB0_303:
	v_cndmask_b32_e64 v128, v156, v158, s[38:39]
	v_lshl_add_u32 v136, v128, 2, v157
	ds_read2_b32 v[128:129], v136 offset1:65
	ds_read2_b32 v[130:131], v136 offset0:130 offset1:195
	v_add_u32_e32 v136, 0x400, v136
	ds_read2_b32 v[192:193], v136 offset0:134 offset1:199
	s_andn2_b64 vcc, exec, s[16:17]
	s_waitcnt lgkmcnt(2)
	v_cvt_pk_bf16_f32 v128, v128, v129
	s_waitcnt lgkmcnt(1)
	v_cvt_pk_bf16_f32 v129, v130, v131
	ds_read2_b32 v[130:131], v136 offset0:4 offset1:69
	v_add_u32_e32 v136, s25, v156
	s_waitcnt lgkmcnt(0)
	v_cvt_pk_bf16_f32 v130, v130, v131
	v_cvt_pk_bf16_f32 v131, v192, v193
	v_mad_i64_i32 v[192:193], s[0:1], v136, s26, 0
	v_lshl_add_u64 v[192:193], v[192:193], 1, s[28:29]
	s_lshl_b64 s[0:1], s[34:35], 1
	v_lshl_add_u64 v[192:193], v[192:193], 0, s[0:1]
	v_lshlrev_b32_e32 v136, 1, v138
	v_lshl_add_u64 v[192:193], v[192:193], 0, v[136:137]
	global_store_dwordx4 v[192:193], v[128:131], off nt
	s_nop 1
	v_cndmask_b32_e64 v128, v159, v160, s[38:39]
	v_lshl_add_u32 v192, v128, 2, v157
	ds_read2_b32 v[128:129], v192 offset1:65
	ds_read2_b32 v[130:131], v192 offset0:130 offset1:195
	v_add_u32_e32 v192, 0x400, v192
	s_waitcnt lgkmcnt(1)
	v_cvt_pk_bf16_f32 v128, v128, v129
	s_waitcnt lgkmcnt(0)
	v_cvt_pk_bf16_f32 v129, v130, v131
	ds_read2_b32 v[130:131], v192 offset0:4 offset1:69
	ds_read2_b32 v[192:193], v192 offset0:134 offset1:199
	s_waitcnt lgkmcnt(1)
	v_cvt_pk_bf16_f32 v130, v130, v131
	s_waitcnt lgkmcnt(0)
	v_cvt_pk_bf16_f32 v131, v192, v193
	v_add_u32_e32 v192, s25, v159
	v_mad_i64_i32 v[192:193], s[18:19], v192, s26, 0
	v_lshl_add_u64 v[192:193], v[192:193], 1, s[28:29]
	v_lshl_add_u64 v[192:193], v[192:193], 0, s[0:1]
	v_lshl_add_u64 v[192:193], v[192:193], 0, v[136:137]
	global_store_dwordx4 v[192:193], v[128:131], off nt
	s_nop 1
	v_cndmask_b32_e64 v128, v161, v162, s[38:39]
	v_lshl_add_u32 v192, v128, 2, v157
	ds_read2_b32 v[128:129], v192 offset1:65
	ds_read2_b32 v[130:131], v192 offset0:130 offset1:195
	v_add_u32_e32 v192, 0x400, v192
	s_waitcnt lgkmcnt(1)
	v_cvt_pk_bf16_f32 v128, v128, v129
	s_waitcnt lgkmcnt(0)
	v_cvt_pk_bf16_f32 v129, v130, v131
	ds_read2_b32 v[130:131], v192 offset0:4 offset1:69
	ds_read2_b32 v[192:193], v192 offset0:134 offset1:199
	s_waitcnt lgkmcnt(1)
	v_cvt_pk_bf16_f32 v130, v130, v131
	s_waitcnt lgkmcnt(0)
	v_cvt_pk_bf16_f32 v131, v192, v193
	v_add_u32_e32 v192, s25, v161
	v_mad_i64_i32 v[192:193], s[18:19], v192, s26, 0
	v_lshl_add_u64 v[192:193], v[192:193], 1, s[28:29]
	v_lshl_add_u64 v[192:193], v[192:193], 0, s[0:1]
	v_lshl_add_u64 v[192:193], v[192:193], 0, v[136:137]
	global_store_dwordx4 v[192:193], v[128:131], off nt
	s_nop 1
	v_cndmask_b32_e64 v128, v163, v164, s[38:39]
	v_lshl_add_u32 v192, v128, 2, v157
	ds_read2_b32 v[128:129], v192 offset1:65
	ds_read2_b32 v[130:131], v192 offset0:130 offset1:195
	v_add_u32_e32 v192, 0x400, v192
	s_waitcnt lgkmcnt(1)
	v_cvt_pk_bf16_f32 v128, v128, v129
	s_waitcnt lgkmcnt(0)
	v_cvt_pk_bf16_f32 v129, v130, v131
	ds_read2_b32 v[130:131], v192 offset0:4 offset1:69
	ds_read2_b32 v[192:193], v192 offset0:134 offset1:199
	s_waitcnt lgkmcnt(1)
	v_cvt_pk_bf16_f32 v130, v130, v131
	s_waitcnt lgkmcnt(0)
	v_cvt_pk_bf16_f32 v131, v192, v193
	v_add_u32_e32 v192, s25, v163
	v_mad_i64_i32 v[192:193], s[18:19], v192, s26, 0
	v_lshl_add_u64 v[192:193], v[192:193], 1, s[28:29]
	v_lshl_add_u64 v[192:193], v[192:193], 0, s[0:1]
	v_lshl_add_u64 v[192:193], v[192:193], 0, v[136:137]
	global_store_dwordx4 v[192:193], v[128:131], off nt
	s_nop 1
	v_cndmask_b32_e64 v128, v165, v166, s[38:39]
	v_lshl_add_u32 v192, v128, 2, v157
	ds_read2_b32 v[128:129], v192 offset1:65
	ds_read2_b32 v[130:131], v192 offset0:130 offset1:195
	v_add_u32_e32 v192, 0x400, v192
	s_waitcnt lgkmcnt(1)
	v_cvt_pk_bf16_f32 v128, v128, v129
	s_waitcnt lgkmcnt(0)
	v_cvt_pk_bf16_f32 v129, v130, v131
	ds_read2_b32 v[130:131], v192 offset0:4 offset1:69
	ds_read2_b32 v[192:193], v192 offset0:134 offset1:199
	s_waitcnt lgkmcnt(1)
	v_cvt_pk_bf16_f32 v130, v130, v131
	s_waitcnt lgkmcnt(0)
	v_cvt_pk_bf16_f32 v131, v192, v193
	v_add_u32_e32 v192, s25, v165
	v_mad_i64_i32 v[192:193], s[18:19], v192, s26, 0
	v_lshl_add_u64 v[192:193], v[192:193], 1, s[28:29]
	v_lshl_add_u64 v[192:193], v[192:193], 0, s[0:1]
	v_lshl_add_u64 v[192:193], v[192:193], 0, v[136:137]
	global_store_dwordx4 v[192:193], v[128:131], off nt
	s_nop 1
	v_cndmask_b32_e64 v128, v167, v168, s[38:39]
	v_lshl_add_u32 v192, v128, 2, v157
	ds_read2_b32 v[128:129], v192 offset1:65
	ds_read2_b32 v[130:131], v192 offset0:130 offset1:195
	v_add_u32_e32 v192, 0x400, v192
	s_waitcnt lgkmcnt(1)
	v_cvt_pk_bf16_f32 v128, v128, v129
	s_waitcnt lgkmcnt(0)
	v_cvt_pk_bf16_f32 v129, v130, v131
	ds_read2_b32 v[130:131], v192 offset0:4 offset1:69
	ds_read2_b32 v[192:193], v192 offset0:134 offset1:199
	s_waitcnt lgkmcnt(1)
	v_cvt_pk_bf16_f32 v130, v130, v131
	s_waitcnt lgkmcnt(0)
	v_cvt_pk_bf16_f32 v131, v192, v193
	v_add_u32_e32 v192, s25, v167
	v_mad_i64_i32 v[192:193], s[18:19], v192, s26, 0
	v_lshl_add_u64 v[192:193], v[192:193], 1, s[28:29]
	v_lshl_add_u64 v[192:193], v[192:193], 0, s[0:1]
	v_lshl_add_u64 v[192:193], v[192:193], 0, v[136:137]
	global_store_dwordx4 v[192:193], v[128:131], off nt
	s_nop 1
	v_cndmask_b32_e64 v128, v169, v170, s[38:39]
	v_lshl_add_u32 v192, v128, 2, v157
	ds_read2_b32 v[128:129], v192 offset1:65
	ds_read2_b32 v[130:131], v192 offset0:130 offset1:195
	v_add_u32_e32 v192, 0x400, v192
	s_waitcnt lgkmcnt(1)
	v_cvt_pk_bf16_f32 v128, v128, v129
	s_waitcnt lgkmcnt(0)
	v_cvt_pk_bf16_f32 v129, v130, v131
	ds_read2_b32 v[130:131], v192 offset0:4 offset1:69
	ds_read2_b32 v[192:193], v192 offset0:134 offset1:199
	s_waitcnt lgkmcnt(1)
	v_cvt_pk_bf16_f32 v130, v130, v131
	s_waitcnt lgkmcnt(0)
	v_cvt_pk_bf16_f32 v131, v192, v193
	v_add_u32_e32 v192, s25, v169
	v_mad_i64_i32 v[192:193], s[18:19], v192, s26, 0
	v_lshl_add_u64 v[192:193], v[192:193], 1, s[28:29]
	v_lshl_add_u64 v[192:193], v[192:193], 0, s[0:1]
	v_lshl_add_u64 v[192:193], v[192:193], 0, v[136:137]
	global_store_dwordx4 v[192:193], v[128:131], off nt
	s_nop 1
	v_cndmask_b32_e64 v128, v171, v172, s[38:39]
	v_lshl_add_u32 v192, v128, 2, v157
	ds_read2_b32 v[128:129], v192 offset1:65
	ds_read2_b32 v[130:131], v192 offset0:130 offset1:195
	v_add_u32_e32 v192, 0x400, v192
	s_waitcnt lgkmcnt(1)
	v_cvt_pk_bf16_f32 v128, v128, v129
	s_waitcnt lgkmcnt(0)
	v_cvt_pk_bf16_f32 v129, v130, v131
	ds_read2_b32 v[130:131], v192 offset0:4 offset1:69
	ds_read2_b32 v[192:193], v192 offset0:134 offset1:199
	s_waitcnt lgkmcnt(1)
	v_cvt_pk_bf16_f32 v130, v130, v131
	s_waitcnt lgkmcnt(0)
	v_cvt_pk_bf16_f32 v131, v192, v193
	v_add_u32_e32 v192, s25, v171
	v_mad_i64_i32 v[192:193], s[18:19], v192, s26, 0
	v_lshl_add_u64 v[192:193], v[192:193], 1, s[28:29]
	v_lshl_add_u64 v[192:193], v[192:193], 0, s[0:1]
	v_lshl_add_u64 v[192:193], v[192:193], 0, v[136:137]
	global_store_dwordx4 v[192:193], v[128:131], off nt
	s_waitcnt lgkmcnt(0)
	s_cbranch_vccnz .LBB0_250
	s_add_i32 s27, s27, s30
	s_cmpk_gt_i32 s27, 0x213f
	s_cbranch_scc1 .LBB0_335
	s_cmpk_gt_i32 s27, 0xbf
	s_cbranch_scc0 .LBB0_319
	s_cmpk_gt_u32 s27, 0x13f
	s_cbranch_scc0 .LBB0_320
	s_cmpk_gt_u32 s27, 0x53f
	s_cbranch_scc0 .LBB0_321
	s_cmpk_gt_u32 s27, 0x73f
	s_cbranch_scc0 .LBB0_322
	s_cmpk_gt_u32 s27, 0xb3f
	s_cbranch_scc0 .LBB0_323
	s_add_i32 s0, s27, 0xf4c0
	s_and_b32 s1, s0, 0xffff
	s_mul_i32 s1, s1, 0xba2f
	s_lshr_b32 s1, s1, 23
	s_mul_i32 s6, s1, 0xb0
	s_sub_i32 s0, s0, s6
	s_lshl_b32 s6, s0, 6
	s_and_b32 s18, s6, 0xffc0
	s_add_i32 s6, s18, 0xffffea00
	s_and_b32 s0, s0, 0xffff
	s_cmpk_lt_u32 s0, 0x58
	s_cselect_b32 s6, s18, s6
	s_lshl_b32 s34, s1, 6
	s_lshl_b32 s1, s6, 1
	s_and_b32 s1, s1, 0x3f00
	s_cmpk_gt_u32 s0, 0x57
	s_cselect_b32 s0, 0x80, 0
	s_and_b32 s6, s6, 64
	s_or_b32 s0, s6, s0
	s_or_b32 s25, s0, s1
	s_lshl_b32 s0, s25, 2
	v_readlane_b32 s1, v255, 11
	s_add_u32 s36, s1, s0
	v_readlane_b32 s0, v255, 12
	s_addc_u32 s37, s0, 0
	s_mov_b64 s[6:7], 0
	s_mov_b64 s[0:1], s[84:85]
	s_branch .LBB0_324
